# accumulator zeroing interleaved into the unit-scheduling scalar chain
# baseline (speedup 1.0000x reference)
; __device__ __forceinline__ void gemm_phase(LAS unsigned char* lds, const Sched& S, const Epi& E) {
;     ...
; #pragma unroll
;         for (int a = 0; a < 2; ++a)
; #pragma unroll
;             for (int b = 0; b < 2; ++b)
; #pragma unroll
;                 for (int m = 0; m < 4; ++m)
; #pragma unroll
;                     for (int n = 0; n < 2; ++n) acc[a][b][m][n] = (f32x4){0.f, 0.f, 0.f, 0.f};
.Lmy_zero_skip:
	v_mov_b64_e32 v[4:5], 0
	v_mov_b64_e32 v[6:7], 0
	v_mov_b64_e32 v[8:9], 0
	v_mov_b64_e32 v[10:11], 0
	v_mov_b64_e32 v[12:13], 0
	v_mov_b64_e32 v[14:15], 0
	v_mov_b64_e32 v[16:17], 0
	v_mov_b64_e32 v[18:19], 0
	v_mov_b64_e32 v[20:21], 0
	v_mov_b64_e32 v[22:23], 0
	v_mov_b64_e32 v[24:25], 0
	v_mov_b64_e32 v[26:27], 0
	v_mov_b64_e32 v[28:29], 0
	v_mov_b64_e32 v[30:31], 0
	v_mov_b64_e32 v[32:33], 0
	v_mov_b64_e32 v[34:35], 0
	v_mov_b64_e32 v[36:37], 0
	v_mov_b64_e32 v[38:39], 0
	v_mov_b64_e32 v[40:41], 0
	v_mov_b64_e32 v[42:43], 0
	v_mov_b64_e32 v[44:45], 0
	v_mov_b64_e32 v[46:47], 0
	v_mov_b64_e32 v[48:49], 0
	v_mov_b64_e32 v[50:51], 0
	v_mov_b64_e32 v[52:53], 0
	v_mov_b64_e32 v[54:55], 0
	v_mov_b64_e32 v[56:57], 0
	v_mov_b64_e32 v[58:59], 0
	v_mov_b64_e32 v[60:61], 0
	v_mov_b64_e32 v[62:63], 0
	v_mov_b64_e32 v[64:65], 0
	v_mov_b64_e32 v[66:67], 0
	v_mov_b64_e32 v[68:69], 0
	v_mov_b64_e32 v[70:71], 0
	v_mov_b64_e32 v[72:73], 0
	v_mov_b64_e32 v[74:75], 0
	v_mov_b64_e32 v[76:77], 0
	v_mov_b64_e32 v[78:79], 0
	v_mov_b64_e32 v[80:81], 0
	v_mov_b64_e32 v[82:83], 0
	v_mov_b64_e32 v[84:85], 0
	v_mov_b64_e32 v[86:87], 0
	v_mov_b64_e32 v[88:89], 0
	v_mov_b64_e32 v[90:91], 0
	v_mov_b64_e32 v[92:93], 0
	v_mov_b64_e32 v[94:95], 0
	v_mov_b64_e32 v[96:97], 0
	v_mov_b64_e32 v[98:99], 0
	v_mov_b64_e32 v[100:101], 0
	v_mov_b64_e32 v[102:103], 0
	v_mov_b64_e32 v[104:105], 0
	v_mov_b64_e32 v[106:107], 0
	v_mov_b64_e32 v[108:109], 0
	v_mov_b64_e32 v[110:111], 0
	v_mov_b64_e32 v[112:113], 0
	v_mov_b64_e32 v[114:115], 0
	v_mov_b64_e32 v[116:117], 0
	v_mov_b64_e32 v[118:119], 0
	v_mov_b64_e32 v[120:121], 0
	v_mov_b64_e32 v[122:123], 0
	v_mov_b64_e32 v[124:125], 0
	v_mov_b64_e32 v[126:127], 0
	v_mov_b64_e32 v[128:129], 0
	s_branch .LBB0_261

;     __device__ __forceinline__ bool next(int i, Unit& u) const {
;         const int sub = (nsub == 2) ? (i & 1) : 0, ii = (nsub == 2) ? (i >> 1) : i;
;         const int nwg = 64 * nN; const long L = (long)ii * G + c; if (L >= nwg) return false;
;         int wgid = (int)L; wgid = (wgid % 8) * (nwg / 8) + wgid / 8;
;         const int nig = 8 * nN, gid = wgid / nig; const int pm = gid * 8 + ((wgid % nig) % 8), pn = (wgid % nig) / 8;
;         const bf16_t* A = sub ? s1.A : s0.A; const bf16_t* B = sub ? s1.B : s0.B;
;         const int lda = sub ? s1.lda : s0.lda, ldb = sub ? s1.ldb : s0.ldb, K = sub ? s1.K : s0.K, mode = sub ? s1.mode : s0.mode, a_pn = sub ? s1.a_pn : s0.a_pn,
;                   bsplit = sub ? s1.bsplit : s0.bsplit, bjump = sub ? s1.bjump : s0.bjump;
;         const int bt = pn < bsplit ? pn : pn + bjump;
;         u.a = (const char*)(A + (size_t)pm * 256 * lda + (size_t)pn * a_pn); u.b = (const char*)(B + (size_t)bt * 256 * ldb);
;         u.lda = lda; u.ldb = ldb; u.nt = K / BK; u.mode = mode; u.pm = pm; u.pn = pn; return true;
; __device__ __forceinline__ void gemm_phase(LAS unsigned char* lds, const Sched& S, const Epi& E) {
;     ...
;         const bool has_next = S.next(ui + 1, nxt);
;         const char* nA = has_next ? nxt.a : cA; const char* nB = has_next ? nxt.b : cB;
;         const int nlda = has_next ? nxt.lda : lda, nldb = has_next ? nxt.ldb : ldb;
;         const size_t hA = (size_t)HALF * lda * 2;
;         const int nt = cur.nt;
;         const int nt_main = has_next ? nt : nt - 2;
.LBB0_259:
	s_add_i32 s15, s2, 1
	s_lshr_b32 s21, s15, s36
	v_readlane_b32 s22, v252, 17
	v_readlane_b32 s26, v252, 3
	s_mul_i32 s22, s21, s22
	s_mul_hi_u32 s24, s21, s26
	s_add_i32 s24, s24, s22
	s_mul_i32 s21, s21, s26
	v_readlane_b32 s22, v252, 0
	v_readlane_b32 s27, v252, 4
	s_add_u32 s26, s21, s22
	v_readlane_b32 s21, v252, 8
	s_addc_u32 s27, s24, s21
	v_mov_b64_e32 v[2:3], s[16:17]
	v_cmp_ge_i64_e64 s[44:45], s[26:27], v[2:3]
	v_cmp_lt_i64_e64 s[42:43], s[26:27], v[2:3]
	s_and_b64 vcc, exec, s[44:45]
	s_mov_b32 s22, s20
	s_cbranch_vccnz .Lmy_zero_skip
	s_ashr_i32 s6, s26, 31
	v_mov_b64_e32 v[4:5], 0
	s_lshr_b32 s6, s6, 29
	v_mov_b64_e32 v[6:7], 0
	s_add_i32 s6, s26, s6
	v_mov_b64_e32 v[8:9], 0
	s_ashr_i32 s7, s6, 3
	v_mov_b64_e32 v[10:11], 0
	s_and_b32 s6, s6, -8
	v_mov_b64_e32 v[12:13], 0
	s_sub_i32 s6, s26, s6
	v_mov_b64_e32 v[14:15], 0
	s_mul_i32 s6, s6, s82
	v_mov_b64_e32 v[16:17], 0
	s_add_i32 s6, s6, s7
	v_mov_b64_e32 v[18:19], 0
	s_abs_i32 s11, s6
	v_mov_b64_e32 v[20:21], 0
	v_readlane_b32 s12, v250, 32
	v_mov_b64_e32 v[22:23], 0
	s_mul_hi_u32 s12, s11, s12
	v_mov_b64_e32 v[24:25], 0
	s_mul_i32 s13, s12, s82
	v_mov_b64_e32 v[26:27], 0
	s_sub_i32 s11, s11, s13
	v_mov_b64_e32 v[28:29], 0
	s_ashr_i32 s7, s6, 31
	v_mov_b64_e32 v[30:31], 0
	s_add_i32 s13, s12, 1
	v_mov_b64_e32 v[32:33], 0
	s_sub_i32 s21, s11, s82
	v_mov_b64_e32 v[34:35], 0
	s_cmp_ge_u32 s11, s82
	v_mov_b64_e32 v[36:37], 0
	s_cselect_b32 s12, s13, s12
	v_mov_b64_e32 v[38:39], 0
	s_cselect_b32 s11, s21, s11
	v_mov_b64_e32 v[40:41], 0
	s_add_i32 s13, s12, 1
	v_mov_b64_e32 v[42:43], 0
	s_cmp_ge_u32 s11, s82
	v_mov_b64_e32 v[44:45], 0
	s_cselect_b32 s11, s13, s12
	v_mov_b64_e32 v[46:47], 0
	s_xor_b32 s11, s11, s7
	v_mov_b64_e32 v[48:49], 0
	s_sub_i32 s7, s11, s7
	v_mov_b64_e32 v[50:51], 0
	s_lshl_b32 s11, s7, 3
	v_mov_b64_e32 v[52:53], 0
	s_mul_i32 s7, s7, s82
	v_mov_b64_e32 v[54:55], 0
	s_sub_i32 s6, s6, s7
	v_mov_b64_e32 v[56:57], 0
	s_ashr_i32 s7, s6, 31
	v_mov_b64_e32 v[58:59], 0
	s_lshr_b32 s7, s7, 29
	v_mov_b64_e32 v[60:61], 0
	s_add_i32 s7, s6, s7
	v_mov_b64_e32 v[62:63], 0
	s_ashr_i32 s94, s7, 3
	v_mov_b64_e32 v[64:65], 0
	s_and_b32 s7, s7, -8
	v_mov_b64_e32 v[66:67], 0
	s_sub_i32 s6, s6, s7
	v_mov_b64_e32 v[68:69], 0
	s_add_i32 s59, s6, s11
	v_mov_b64_e32 v[70:71], 0
	s_bitcmp0_b32 s2, 0
	v_mov_b64_e32 v[72:73], 0
	v_readlane_b32 s12, v250, 21
	v_mov_b64_e32 v[74:75], 0
	s_cselect_b64 s[6:7], -1, 0
	v_mov_b64_e32 v[76:77], 0
	v_readlane_b32 s13, v250, 22
	v_mov_b64_e32 v[78:79], 0
	s_and_b64 s[26:27], s[12:13], s[6:7]
	v_mov_b64_e32 v[80:81], 0
	s_and_b64 s[6:7], s[26:27], exec
	v_mov_b64_e32 v[82:83], 0
	v_readlane_b32 s6, v250, 15
	v_mov_b64_e32 v[84:85], 0
	v_readlane_b32 s7, v250, 16
	v_mov_b64_e32 v[86:87], 0
	s_cselect_b32 s21, s7, s47
	v_mov_b64_e32 v[88:89], 0
	s_cselect_b32 s24, s6, s46
	v_mov_b64_e32 v[90:91], 0
	v_readlane_b32 s6, v250, 12
	v_mov_b64_e32 v[92:93], 0
	v_readlane_b32 s7, v250, 19
	v_mov_b64_e32 v[94:95], 0
	s_cselect_b32 s22, s7, s6
	v_mov_b64_e32 v[96:97], 0
	v_readlane_b32 s6, v250, 20
	v_mov_b64_e32 v[98:99], 0
	s_cselect_b32 s11, 0x400, s6
	v_mov_b64_e32 v[100:101], 0
	v_readlane_b32 s6, v250, 13
	v_mov_b64_e32 v[102:103], 0
	v_readlane_b32 s7, v250, 14
	v_mov_b64_e32 v[104:105], 0
	s_cselect_b32 s58, s7, s6
	v_mov_b64_e32 v[106:107], 0
	v_readlane_b32 s6, v250, 17
	v_mov_b64_e32 v[108:109], 0
	s_cselect_b32 s2, s51, s85
	v_mov_b64_e32 v[110:111], 0
	s_cselect_b32 s12, s50, s84
	v_mov_b64_e32 v[112:113], 0
	s_cmp_gt_i32 s6, s94
	v_mov_b64_e32 v[114:115], 0
	s_cselect_b64 s[6:7], -1, 0
	v_mov_b64_e32 v[116:117], 0
	s_or_b64 s[6:7], s[26:27], s[6:7]
	v_mov_b64_e32 v[118:119], 0
	s_and_b64 s[6:7], s[6:7], exec
	v_mov_b64_e32 v[120:121], 0
	v_readlane_b32 s6, v250, 18
	v_mov_b64_e32 v[122:123], 0
	s_cselect_b32 s6, 0, s6
	v_mov_b64_e32 v[124:125], 0
	s_add_i32 s28, s6, s94
	v_mov_b64_e32 v[126:127], 0
	s_lshl_b32 s6, s22, 8
	v_mov_b64_e32 v[128:129], 0
	s_mul_hi_i32 s7, s6, s59
	s_mul_i32 s6, s6, s59
	s_lshl_b64 s[6:7], s[6:7], 1
	s_add_u32 s12, s12, s6
	s_addc_u32 s2, s2, s7
	s_ashr_i32 s13, s94, 31
	s_and_b64 s[6:7], s[26:27], exec
	s_cselect_b32 s29, 0, s88
	s_cselect_b32 s6, 0, s89
	s_mul_i32 s7, s29, s13
	s_mul_hi_u32 s13, s29, s94
	s_add_i32 s7, s13, s7
	s_mul_i32 s6, s6, s94
	s_add_i32 s7, s7, s6
	s_mul_i32 s6, s29, s94
	s_lshl_b64 s[6:7], s[6:7], 1
	s_add_u32 s6, s12, s6
	s_addc_u32 s7, s2, s7
	s_lshl_b32 s2, s11, 8
	s_mul_hi_i32 s13, s28, s2
	s_mul_i32 s12, s28, s2
	s_lshl_b64 s[12:13], s[12:13], 1
	s_add_u32 s12, s24, s12
	s_addc_u32 s13, s21, s13
	s_and_b64 s[26:27], s[26:27], exec
	v_readlane_b32 s2, v250, 31
	s_cselect_b32 s33, 16, s2
.LBB0_261:
	s_mov_b32 s21, s31
	s_lshl_b64 s[66:67], s[20:21], 8
	s_add_i32 s21, s60, -2
	s_and_b64 s[26:27], s[42:43], exec
	s_cselect_b32 s68, s60, s21
	s_cmp_lt_i32 s68, 1
	s_cbranch_scc1 .LBB0_274
	s_add_u32 vcc_lo, s96, 0x80
	s_addc_u32 vcc_hi, s97, 0
	s_add_u32 s2, s8, 0x100
	s_addc_u32 s72, s9, 0
	v_mad_u64_u32 v[2:3], s[8:9], s20, v235, v[206:207]
	v_mov_b32_e32 v3, v1
	s_waitcnt lgkmcnt(0)
	v_lshl_add_u64 v[130:131], s[66:67], 0, v[2:3]
	v_mad_u64_u32 v[2:3], s[8:9], s20, v236, v[208:209]
	v_mov_b32_e32 v3, v1
	v_lshl_add_u64 v[132:133], s[66:67], 0, v[2:3]
	s_mov_b32 s3, s92
	s_mov_b32 s8, 0
	v_mov_b64_e32 v[2:3], 0
; #define PG8_LDA(dst, b, h) do { _Pragma("unroll") for (int m = 0; m < 4; ++m) _Pragma("unroll") for (int k = 0; k < 2; ++k) dst[m][k] = *(const LAS bf16x8*)(lds + PG8_SA(b, h) + aoff + m * 2048 + k * 1024); } while (0)
; #define PG8_LDB(dst, b, h) do { _Pragma("unroll") for (int n = 0; n < 2; ++n) _Pragma("unroll") for (int k = 0; k < 2; ++k) dst[n][k] = *(const LAS bf16x8*)(lds + PG8_SB(b, h) + boff + n * 2048 + k * 1024); } while (0)
; #define PG8_MMA(ai, bj, At, Bt) do { __builtin_amdgcn_s_setprio(1); _Pragma("unroll") for (int m = 0; m < 4; ++m) _Pragma("unroll") for (int n = 0; n < 2; ++n) _Pragma("unroll") for (int k = 0; k < 2; ++k) \
;         acc[ai][bj][m][n] = __builtin_amdgcn_mfma_f32_16x16x32_bf16(Bt[n][k], At[m][k], acc[ai][bj][m][n], 0, 0, 0); __builtin_amdgcn_s_setprio(0); } while (0)
; #define PG8_WAIT_V(n) asm volatile("s_waitcnt vmcnt(" #n ")" ::: "memory")
; #define PG8_WAIT_L(n) asm volatile("s_waitcnt lgkmcnt(" #n ")" ::: "memory")
; #define PG8_BAR __builtin_amdgcn_s_barrier()
; #define PG8_SCHED __builtin_amdgcn_sched_barrier(0)
; #define PG8_STA(bufoff, gbase, ld) PG8_STAGE(bufoff, gbase, RA0 * (unsigned)(ld) + CC0, RA1 * (unsigned)(ld) + CC1)
; __device__ __forceinline__ void gemm_phase(LAS unsigned char* lds, const Sched& S, const Epi& E) {
;     ...
;         for (int t = 0; t < nt_main; t += 2) {
;             const bool last = (t == nt - 2);
;             const char* a1 = cA + (size_t)(t + 1) * kstep;
;             const char* a2 = last ? nA : cA + (size_t)(t + 2) * kstep; const char* b2 = last ? nB : cB + (size_t)(t + 2) * kstep;
;             const char* a3 = a2 + kstep; const char* b3 = b2 + kstep;
;             const int xlda = last ? nlda : lda, xldb = last ? nldb : ldb;
;             const size_t xhA = (size_t)HALF * xlda * 2, xhB = (size_t)HALF * xldb * 2;
;             PG8_LDB(B0, 0, 0); PG8_LDB(B1, 0, 1); PG8_SCHED; PG8_LDA(At, 0, 0); PG8_STA(PG8_SA(1, 1), a1 + hA, lda);
;             PG8_WAIT_V(8); PG8_WAIT_L(0); PG8_BAR; PG8_MMA(0, 0, At, B0); PG8_MMA(0, 1, At, B1); PG8_BAR; PG8_SCHED;
;             PG8_LDA(At, 0, 1); PG8_STB(PG8_SB(0, 0), b2, xldb); PG8_STB(PG8_SB(0, 1), b2 + xhB, xldb); PG8_STA(PG8_SA(0, 0), a2, xlda);
;             PG8_WAIT_V(8); PG8_WAIT_L(0); PG8_BAR; PG8_MMA(1, 0, At, B0); PG8_MMA(1, 1, At, B1); PG8_BAR; PG8_SCHED;
.LBB0_263:
	s_add_i32 s24, s8, 2
	s_add_u32 s26, vcc_lo, 0x80
	s_addc_u32 s9, vcc_hi, 0
	s_add_i32 s37, 0, 0x10000
	s_cmp_eq_u32 s21, s8
	s_cselect_b32 s9, s7, s9
	s_cselect_b32 s8, s6, s26
	s_cselect_b32 s92, s11, s61
	s_cselect_b32 s30, s22, s20
	v_add_u32_e32 v0, s37, v241
	s_cselect_b32 s29, s13, s72
	s_cselect_b32 s28, s12, s2
	s_add_i32 s57, 0, 0x14000
	ds_read_b128 v[134:137], v0
	ds_read_b128 v[138:141], v0 offset:1024
	ds_read_b128 v[142:145], v0 offset:2048
	ds_read_b128 v[146:149], v0 offset:3072
	v_add_u32_e32 v0, s57, v241
	ds_read_b128 v[150:153], v0
	ds_read_b128 v[154:157], v0 offset:1024
	ds_read_b128 v[158:161], v0 offset:2048
	ds_read_b128 v[162:165], v0 offset:3072
	s_mov_b32 s93, s31
	s_lshl_b64 s[26:27], s[30:31], 8
	v_add_u32_e32 v0, 0, v240
	v_lshl_add_u64 v[214:215], vcc, 0, v[130:131]
	s_add_i32 m0, s34, 0xc000
	ds_read_b128 v[166:169], v0
	ds_read_b128 v[170:173], v0 offset:1024
	ds_read_b128 v[174:177], v0 offset:2048
	ds_read_b128 v[178:181], v0 offset:3072
	ds_read_b128 v[182:185], v0 offset:4096
	ds_read_b128 v[186:189], v0 offset:5120
	ds_read_b128 v[190:193], v0 offset:6144
	ds_read_b128 v[210:213], v0 offset:7168
	global_load_lds_dwordx4 v[214:215], off
	v_lshl_add_u64 v[214:215], vcc, 0, v[132:133]
	s_add_i32 m0, s34, 0xe000
	s_nop 0
	global_load_lds_dwordx4 v[214:215], off
	s_waitcnt vmcnt(8)
	s_waitcnt lgkmcnt(0)
	s_barrier
	s_setprio 1
	s_waitcnt lgkmcnt(0)
	v_mfma_f32_16x16x32_bf16 v[126:129], v[134:137], v[166:169], v[126:129]
	v_mfma_f32_16x16x32_bf16 v[122:125], v[142:145], v[166:169], v[122:125]
	v_mfma_f32_16x16x32_bf16 v[110:113], v[134:137], v[174:177], v[110:113]
	v_mfma_f32_16x16x32_bf16 v[106:109], v[142:145], v[174:177], v[106:109]
	v_mfma_f32_16x16x32_bf16 v[98:101], v[134:137], v[182:185], v[98:101]
	v_mfma_f32_16x16x32_bf16 v[90:93], v[142:145], v[182:185], v[90:93]
	v_mfma_f32_16x16x32_bf16 v[82:85], v[134:137], v[190:193], v[82:85]
	v_mfma_f32_16x16x32_bf16 v[74:77], v[142:145], v[190:193], v[74:77]
	v_mfma_f32_16x16x32_bf16 v[126:129], v[138:141], v[170:173], v[126:129]
	v_mfma_f32_16x16x32_bf16 v[122:125], v[146:149], v[170:173], v[122:125]
	v_mfma_f32_16x16x32_bf16 v[110:113], v[138:141], v[178:181], v[110:113]
	v_mfma_f32_16x16x32_bf16 v[106:109], v[146:149], v[178:181], v[106:109]
	v_mfma_f32_16x16x32_bf16 v[98:101], v[138:141], v[186:189], v[98:101]
	v_mfma_f32_16x16x32_bf16 v[90:93], v[146:149], v[186:189], v[90:93]
	v_mfma_f32_16x16x32_bf16 v[82:85], v[138:141], v[210:213], v[82:85]
	v_mfma_f32_16x16x32_bf16 v[74:77], v[146:149], v[210:213], v[74:77]
	s_setprio 0
	s_setprio 1
	v_mfma_f32_16x16x32_bf16 v[118:121], v[150:153], v[166:169], v[118:121]
	v_mfma_f32_16x16x32_bf16 v[114:117], v[158:161], v[166:169], v[114:117]
	v_mfma_f32_16x16x32_bf16 v[102:105], v[150:153], v[174:177], v[102:105]
	v_mfma_f32_16x16x32_bf16 v[94:97], v[158:161], v[174:177], v[94:97]
	v_mfma_f32_16x16x32_bf16 v[86:89], v[150:153], v[182:185], v[86:89]
	v_mfma_f32_16x16x32_bf16 v[78:81], v[158:161], v[182:185], v[78:81]
	v_mfma_f32_16x16x32_bf16 v[70:73], v[150:153], v[190:193], v[70:73]
	v_mfma_f32_16x16x32_bf16 v[66:69], v[158:161], v[190:193], v[66:69]
	v_mfma_f32_16x16x32_bf16 v[118:121], v[154:157], v[170:173], v[118:121]
	v_mfma_f32_16x16x32_bf16 v[114:117], v[162:165], v[170:173], v[114:117]
	v_mfma_f32_16x16x32_bf16 v[102:105], v[154:157], v[178:181], v[102:105]
	v_mfma_f32_16x16x32_bf16 v[94:97], v[162:165], v[178:181], v[94:97]
	v_mfma_f32_16x16x32_bf16 v[86:89], v[154:157], v[186:189], v[86:89]
	v_mfma_f32_16x16x32_bf16 v[78:81], v[162:165], v[186:189], v[78:81]
	v_mfma_f32_16x16x32_bf16 v[70:73], v[154:157], v[210:213], v[70:73]
	v_mfma_f32_16x16x32_bf16 v[66:69], v[162:165], v[210:213], v[66:69]
	s_setprio 0
	s_barrier
	s_add_i32 s37, s37, s25
	v_mad_u64_u32 v[214:215], s[80:81], s92, v237, v[194:195]
	s_mov_b32 m0, s37
	ds_read_b128 v[166:169], v0 offset:16384
	ds_read_b128 v[170:173], v0 offset:17408
	ds_read_b128 v[174:177], v0 offset:18432
	ds_read_b128 v[178:181], v0 offset:19456
	ds_read_b128 v[182:185], v0 offset:20480
	ds_read_b128 v[186:189], v0 offset:21504
	ds_read_b128 v[190:193], v0 offset:22528
	ds_read_b128 v[210:213], v0 offset:23552
	s_lshl_b64 s[74:75], s[92:93], 8
	global_load_lds_dwordx4 v214, s[28:29]
	s_add_i32 m0, s37, 0x2000
	s_add_u32 s74, s28, s74
	v_mad_u64_u32 v[216:217], s[80:81], s92, v238, v[196:197]
	s_addc_u32 s75, s29, s75
	s_add_i32 s37, s57, s25
	global_load_lds_dwordx4 v216, s[28:29]
	s_mov_b32 m0, s37
	v_mad_u64_u32 v[218:219], s[80:81], s30, v235, v[194:195]
	global_load_lds_dwordx4 v214, s[74:75]
	s_add_i32 m0, s37, 0x2000
	v_mad_u64_u32 v[220:221], s[80:81], s30, v236, v[196:197]
	global_load_lds_dwordx4 v216, s[74:75]
	s_mov_b32 m0, s34
	v_mov_b32_e32 v215, v1
	global_load_lds_dwordx4 v218, s[8:9]
	s_mov_b32 m0, s35
	v_mov_b32_e32 v217, v1
	global_load_lds_dwordx4 v220, s[8:9]
	v_mov_b32_e32 v219, v1
	v_mov_b32_e32 v221, v1
	v_lshl_add_u64 v[222:223], s[28:29], 0, v[214:215]
	v_lshl_add_u64 v[224:225], s[28:29], 0, v[216:217]
	v_lshl_add_u64 v[214:215], s[74:75], 0, v[214:215]
	v_lshl_add_u64 v[216:217], s[74:75], 0, v[216:217]
	v_lshl_add_u64 v[226:227], s[8:9], 0, v[218:219]
	v_lshl_add_u64 v[228:229], s[8:9], 0, v[220:221]
	s_waitcnt vmcnt(8)
	s_waitcnt lgkmcnt(0)
	s_barrier
; #define PG8_LDA(dst, b, h) do { _Pragma("unroll") for (int m = 0; m < 4; ++m) _Pragma("unroll") for (int k = 0; k < 2; ++k) dst[m][k] = *(const LAS bf16x8*)(lds + PG8_SA(b, h) + aoff + m * 2048 + k * 1024); } while (0)
; #define PG8_LDB(dst, b, h) do { _Pragma("unroll") for (int n = 0; n < 2; ++n) _Pragma("unroll") for (int k = 0; k < 2; ++k) dst[n][k] = *(const LAS bf16x8*)(lds + PG8_SB(b, h) + boff + n * 2048 + k * 1024); } while (0)
; #define PG8_MMA(ai, bj, At, Bt) do { __builtin_amdgcn_s_setprio(1); _Pragma("unroll") for (int m = 0; m < 4; ++m) _Pragma("unroll") for (int n = 0; n < 2; ++n) _Pragma("unroll") for (int k = 0; k < 2; ++k) \
;         acc[ai][bj][m][n] = __builtin_amdgcn_mfma_f32_16x16x32_bf16(Bt[n][k], At[m][k], acc[ai][bj][m][n], 0, 0, 0); __builtin_amdgcn_s_setprio(0); } while (0)
; #define PG8_WAIT_V(n) asm volatile("s_waitcnt vmcnt(" #n ")" ::: "memory")
; #define PG8_WAIT_L(n) asm volatile("s_waitcnt lgkmcnt(" #n ")" ::: "memory")
; #define PG8_BAR __builtin_amdgcn_s_barrier()
; #define PG8_SCHED __builtin_amdgcn_sched_barrier(0)
; #define PG8_STA(bufoff, gbase, ld) PG8_STAGE(bufoff, gbase, RA0 * (unsigned)(ld) + CC0, RA1 * (unsigned)(ld) + CC1)
; __device__ __forceinline__ void gemm_phase(LAS unsigned char* lds, const Sched& S, const Epi& E) {
;     ...
;             PG8_WAIT_V(8); PG8_WAIT_L(0); PG8_BAR; PG8_MMA(1, 0, At, B0); PG8_MMA(1, 1, At, B1); PG8_BAR; PG8_SCHED;
;             PG8_LDB(B0, 1, 0); PG8_LDB(B1, 1, 1); PG8_SCHED; PG8_LDA(At, 1, 0); PG8_STA(PG8_SA(0, 1), a2 + xhA, xlda);
;             PG8_WAIT_V(8); PG8_WAIT_L(0); PG8_BAR; PG8_MMA(0, 0, At, B0); PG8_MMA(0, 1, At, B1); PG8_BAR; PG8_SCHED;
	s_setprio 1
	s_waitcnt lgkmcnt(0)
	v_mfma_f32_16x16x32_bf16 v[62:65], v[134:137], v[166:169], v[62:65]
	v_mfma_f32_16x16x32_bf16 v[58:61], v[142:145], v[166:169], v[58:61]
	v_mfma_f32_16x16x32_bf16 v[46:49], v[134:137], v[174:177], v[46:49]
	v_mfma_f32_16x16x32_bf16 v[42:45], v[142:145], v[174:177], v[42:45]
	v_mfma_f32_16x16x32_bf16 v[30:33], v[134:137], v[182:185], v[30:33]
	v_mfma_f32_16x16x32_bf16 v[26:29], v[142:145], v[182:185], v[26:29]
	v_mfma_f32_16x16x32_bf16 v[14:17], v[134:137], v[190:193], v[14:17]
	v_mfma_f32_16x16x32_bf16 v[10:13], v[142:145], v[190:193], v[10:13]
	v_mfma_f32_16x16x32_bf16 v[62:65], v[138:141], v[170:173], v[62:65]
	v_mfma_f32_16x16x32_bf16 v[58:61], v[146:149], v[170:173], v[58:61]
	v_mfma_f32_16x16x32_bf16 v[46:49], v[138:141], v[178:181], v[46:49]
	v_mfma_f32_16x16x32_bf16 v[42:45], v[146:149], v[178:181], v[42:45]
	v_mfma_f32_16x16x32_bf16 v[30:33], v[138:141], v[186:189], v[30:33]
	v_mfma_f32_16x16x32_bf16 v[26:29], v[146:149], v[186:189], v[26:29]
	v_mfma_f32_16x16x32_bf16 v[14:17], v[138:141], v[210:213], v[14:17]
	v_mfma_f32_16x16x32_bf16 v[10:13], v[146:149], v[210:213], v[10:13]
	s_setprio 0
	s_setprio 1
	v_mfma_f32_16x16x32_bf16 v[54:57], v[150:153], v[166:169], v[54:57]
	v_mfma_f32_16x16x32_bf16 v[50:53], v[158:161], v[166:169], v[50:53]
	v_mfma_f32_16x16x32_bf16 v[38:41], v[150:153], v[174:177], v[38:41]
	v_mfma_f32_16x16x32_bf16 v[34:37], v[158:161], v[174:177], v[34:37]
	v_mfma_f32_16x16x32_bf16 v[22:25], v[150:153], v[182:185], v[22:25]
	v_mfma_f32_16x16x32_bf16 v[18:21], v[158:161], v[182:185], v[18:21]
	v_mfma_f32_16x16x32_bf16 v[6:9], v[150:153], v[190:193], v[6:9]
	v_mfma_f32_16x16x32_bf16 v[2:5], v[158:161], v[190:193], v[2:5]
	v_mfma_f32_16x16x32_bf16 v[54:57], v[154:157], v[170:173], v[54:57]
	v_mfma_f32_16x16x32_bf16 v[50:53], v[162:165], v[170:173], v[50:53]
	v_mfma_f32_16x16x32_bf16 v[38:41], v[154:157], v[178:181], v[38:41]
	v_mfma_f32_16x16x32_bf16 v[34:37], v[162:165], v[178:181], v[34:37]
	v_mfma_f32_16x16x32_bf16 v[22:25], v[154:157], v[186:189], v[22:25]
	v_mfma_f32_16x16x32_bf16 v[18:21], v[162:165], v[186:189], v[18:21]
	v_mfma_f32_16x16x32_bf16 v[6:9], v[154:157], v[210:213], v[6:9]
	v_mfma_f32_16x16x32_bf16 v[2:5], v[162:165], v[210:213], v[2:5]
	s_setprio 0
	s_barrier
	s_add_i32 s28, 0, 0x18000
	s_add_i32 s29, 0, 0x1c000
	v_add_u32_e32 v146, s28, v241
	v_add_u32_e32 v162, s29, v241
	ds_read_b128 v[134:137], v146
	ds_read_b128 v[138:141], v146 offset:1024
	ds_read_b128 v[142:145], v146 offset:2048
	ds_read_b128 v[146:149], v146 offset:3072
	ds_read_b128 v[150:153], v162
	ds_read_b128 v[154:157], v162 offset:1024
	ds_read_b128 v[158:161], v162 offset:2048
	ds_read_b128 v[162:165], v162 offset:3072
	s_add_u32 s8, s8, s26
	s_addc_u32 s9, s9, s27
	s_mov_b32 m0, s39
	ds_read_b128 v[166:169], v0 offset:32768
	ds_read_b128 v[170:173], v0 offset:33792
	ds_read_b128 v[174:177], v0 offset:34816
	ds_read_b128 v[178:181], v0 offset:35840
	ds_read_b128 v[182:185], v0 offset:36864
	ds_read_b128 v[186:189], v0 offset:37888
	ds_read_b128 v[190:193], v0 offset:38912
	ds_read_b128 v[210:213], v0 offset:39936
	global_load_lds_dwordx4 v218, s[8:9]
	s_mov_b32 m0, s91
	s_nop 0
	global_load_lds_dwordx4 v220, s[8:9]
	s_waitcnt vmcnt(8)
	s_waitcnt lgkmcnt(0)
	s_barrier
	s_setprio 1
	s_waitcnt lgkmcnt(0)
	v_mfma_f32_16x16x32_bf16 v[126:129], v[134:137], v[166:169], v[126:129]
	v_mfma_f32_16x16x32_bf16 v[122:125], v[142:145], v[166:169], v[122:125]
	v_mfma_f32_16x16x32_bf16 v[110:113], v[134:137], v[174:177], v[110:113]
	v_mfma_f32_16x16x32_bf16 v[106:109], v[142:145], v[174:177], v[106:109]
	v_mfma_f32_16x16x32_bf16 v[98:101], v[134:137], v[182:185], v[98:101]
	v_mfma_f32_16x16x32_bf16 v[90:93], v[142:145], v[182:185], v[90:93]
	v_mfma_f32_16x16x32_bf16 v[82:85], v[134:137], v[190:193], v[82:85]
	v_mfma_f32_16x16x32_bf16 v[74:77], v[142:145], v[190:193], v[74:77]
	v_mfma_f32_16x16x32_bf16 v[126:129], v[138:141], v[170:173], v[126:129]
	v_mfma_f32_16x16x32_bf16 v[122:125], v[146:149], v[170:173], v[122:125]
	v_mfma_f32_16x16x32_bf16 v[110:113], v[138:141], v[178:181], v[110:113]
	v_mfma_f32_16x16x32_bf16 v[106:109], v[146:149], v[178:181], v[106:109]
	v_mfma_f32_16x16x32_bf16 v[98:101], v[138:141], v[186:189], v[98:101]
	v_mfma_f32_16x16x32_bf16 v[90:93], v[146:149], v[186:189], v[90:93]
	v_mfma_f32_16x16x32_bf16 v[82:85], v[138:141], v[210:213], v[82:85]
	v_mfma_f32_16x16x32_bf16 v[74:77], v[146:149], v[210:213], v[74:77]
	s_setprio 0
	s_setprio 1
	v_mfma_f32_16x16x32_bf16 v[118:121], v[150:153], v[166:169], v[118:121]
	v_mfma_f32_16x16x32_bf16 v[114:117], v[158:161], v[166:169], v[114:117]
	v_mfma_f32_16x16x32_bf16 v[102:105], v[150:153], v[174:177], v[102:105]
	v_mfma_f32_16x16x32_bf16 v[94:97], v[158:161], v[174:177], v[94:97]
	v_mfma_f32_16x16x32_bf16 v[86:89], v[150:153], v[182:185], v[86:89]
	v_mfma_f32_16x16x32_bf16 v[78:81], v[158:161], v[182:185], v[78:81]
	v_mfma_f32_16x16x32_bf16 v[70:73], v[150:153], v[190:193], v[70:73]
	v_mfma_f32_16x16x32_bf16 v[66:69], v[158:161], v[190:193], v[66:69]
	v_mfma_f32_16x16x32_bf16 v[118:121], v[154:157], v[170:173], v[118:121]
	v_mfma_f32_16x16x32_bf16 v[114:117], v[162:165], v[170:173], v[114:117]
	v_mfma_f32_16x16x32_bf16 v[102:105], v[154:157], v[178:181], v[102:105]
	v_mfma_f32_16x16x32_bf16 v[94:97], v[162:165], v[178:181], v[94:97]
	v_mfma_f32_16x16x32_bf16 v[86:89], v[154:157], v[186:189], v[86:89]
	v_mfma_f32_16x16x32_bf16 v[78:81], v[162:165], v[186:189], v[78:81]
	v_mfma_f32_16x16x32_bf16 v[70:73], v[154:157], v[210:213], v[70:73]
	v_mfma_f32_16x16x32_bf16 v[66:69], v[162:165], v[210:213], v[66:69]
	s_setprio 0
	s_barrier
; #define PG8_LDA(dst, b, h) do { _Pragma("unroll") for (int m = 0; m < 4; ++m) _Pragma("unroll") for (int k = 0; k < 2; ++k) dst[m][k] = *(const LAS bf16x8*)(lds + PG8_SA(b, h) + aoff + m * 2048 + k * 1024); } while (0)
; #define PG8_MMA(ai, bj, At, Bt) do { __builtin_amdgcn_s_setprio(1); _Pragma("unroll") for (int m = 0; m < 4; ++m) _Pragma("unroll") for (int n = 0; n < 2; ++n) _Pragma("unroll") for (int k = 0; k < 2; ++k) \
;         acc[ai][bj][m][n] = __builtin_amdgcn_mfma_f32_16x16x32_bf16(Bt[n][k], At[m][k], acc[ai][bj][m][n], 0, 0, 0); __builtin_amdgcn_s_setprio(0); } while (0)
; #define PG8_WAIT_V(n) asm volatile("s_waitcnt vmcnt(" #n ")" ::: "memory")
; #define PG8_WAIT_L(n) asm volatile("s_waitcnt lgkmcnt(" #n ")" ::: "memory")
; #define PG8_BAR __builtin_amdgcn_s_barrier()
; #define PG8_SCHED __builtin_amdgcn_sched_barrier(0)
; #define PG8_STA(bufoff, gbase, ld) PG8_STAGE(bufoff, gbase, RA0 * (unsigned)(ld) + CC0, RA1 * (unsigned)(ld) + CC1)
; #define PG8_STB(bufoff, gbase, ld) PG8_STAGE(bufoff, gbase, RB0 * (unsigned)(ld) + CC0, RB1 * (unsigned)(ld) + CC1)
; __device__ __forceinline__ void gemm_phase(LAS unsigned char* lds, const Sched& S, const Epi& E) {
;     ...
;             PG8_LDA(At, 1, 1); PG8_STB(PG8_SB(1, 0), b3, xldb); PG8_STB(PG8_SB(1, 1), b3 + xhB, xldb); PG8_STA(PG8_SA(1, 0), a3, xlda);
;             PG8_WAIT_V(8); PG8_WAIT_L(0); PG8_BAR; PG8_MMA(1, 0, At, B0); PG8_MMA(1, 1, At, B1); PG8_BAR; PG8_SCHED;
;         }
;         if (!has_next) {
	s_add_i32 s8, s28, s25
	v_lshl_add_u64 v[218:219], v[222:223], 0, s[52:53]
	s_mov_b32 m0, s8
	ds_read_b128 v[166:169], v0 offset:49152
	ds_read_b128 v[170:173], v0 offset:50176
	ds_read_b128 v[174:177], v0 offset:51200
	ds_read_b128 v[178:181], v0 offset:52224
	ds_read_b128 v[182:185], v0 offset:53248
	ds_read_b128 v[186:189], v0 offset:54272
	ds_read_b128 v[190:193], v0 offset:55296
	ds_read_b128 v[210:213], v0 offset:56320
	global_load_lds_dwordx4 v[218:219], off
	v_lshl_add_u64 v[218:219], v[224:225], 0, s[52:53]
	s_add_i32 m0, s8, 0x2000
	s_add_i32 s8, s29, s25
	global_load_lds_dwordx4 v[218:219], off
	v_lshl_add_u64 v[214:215], v[214:215], 0, s[52:53]
	s_mov_b32 m0, s8
	s_nop 0
	global_load_lds_dwordx4 v[214:215], off
	v_lshl_add_u64 v[214:215], v[216:217], 0, s[52:53]
	s_add_i32 m0, s8, 0x2000
	s_nop 0
	global_load_lds_dwordx4 v[214:215], off
	v_lshl_add_u64 v[214:215], v[226:227], 0, s[52:53]
	s_mov_b32 m0, s90
	s_nop 0
	global_load_lds_dwordx4 v[214:215], off
	v_lshl_add_u64 v[214:215], v[228:229], 0, s[52:53]
	s_mov_b32 m0, s73
	s_nop 0
	global_load_lds_dwordx4 v[214:215], off
	s_waitcnt vmcnt(8)
	s_waitcnt lgkmcnt(0)
	s_barrier
	s_setprio 1
	s_waitcnt lgkmcnt(0)
	v_mfma_f32_16x16x32_bf16 v[62:65], v[134:137], v[166:169], v[62:65]
	v_mfma_f32_16x16x32_bf16 v[58:61], v[142:145], v[166:169], v[58:61]
	v_mfma_f32_16x16x32_bf16 v[46:49], v[134:137], v[174:177], v[46:49]
	v_mfma_f32_16x16x32_bf16 v[42:45], v[142:145], v[174:177], v[42:45]
	v_mfma_f32_16x16x32_bf16 v[30:33], v[134:137], v[182:185], v[30:33]
	v_mfma_f32_16x16x32_bf16 v[26:29], v[142:145], v[182:185], v[26:29]
	v_mfma_f32_16x16x32_bf16 v[14:17], v[134:137], v[190:193], v[14:17]
	v_mfma_f32_16x16x32_bf16 v[10:13], v[142:145], v[190:193], v[10:13]
	v_mfma_f32_16x16x32_bf16 v[62:65], v[138:141], v[170:173], v[62:65]
	v_mfma_f32_16x16x32_bf16 v[58:61], v[146:149], v[170:173], v[58:61]
	v_mfma_f32_16x16x32_bf16 v[46:49], v[138:141], v[178:181], v[46:49]
	v_mfma_f32_16x16x32_bf16 v[42:45], v[146:149], v[178:181], v[42:45]
	v_mfma_f32_16x16x32_bf16 v[30:33], v[138:141], v[186:189], v[30:33]
	v_mfma_f32_16x16x32_bf16 v[26:29], v[146:149], v[186:189], v[26:29]
	v_mfma_f32_16x16x32_bf16 v[14:17], v[138:141], v[210:213], v[14:17]
	v_mfma_f32_16x16x32_bf16 v[10:13], v[146:149], v[210:213], v[10:13]
	s_setprio 0
	s_setprio 1
	v_mfma_f32_16x16x32_bf16 v[54:57], v[150:153], v[166:169], v[54:57]
	v_mfma_f32_16x16x32_bf16 v[50:53], v[158:161], v[166:169], v[50:53]
	v_mfma_f32_16x16x32_bf16 v[38:41], v[150:153], v[174:177], v[38:41]
	v_mfma_f32_16x16x32_bf16 v[34:37], v[158:161], v[174:177], v[34:37]
	v_mfma_f32_16x16x32_bf16 v[22:25], v[150:153], v[182:185], v[22:25]
	v_mfma_f32_16x16x32_bf16 v[18:21], v[158:161], v[182:185], v[18:21]
	v_mfma_f32_16x16x32_bf16 v[6:9], v[150:153], v[190:193], v[6:9]
	v_mfma_f32_16x16x32_bf16 v[2:5], v[158:161], v[190:193], v[2:5]
	v_mfma_f32_16x16x32_bf16 v[54:57], v[154:157], v[170:173], v[54:57]
	v_mfma_f32_16x16x32_bf16 v[50:53], v[162:165], v[170:173], v[50:53]
	v_mfma_f32_16x16x32_bf16 v[38:41], v[154:157], v[178:181], v[38:41]
	v_mfma_f32_16x16x32_bf16 v[34:37], v[162:165], v[178:181], v[34:37]
	v_mfma_f32_16x16x32_bf16 v[22:25], v[154:157], v[186:189], v[22:25]
	v_mfma_f32_16x16x32_bf16 v[18:21], v[162:165], v[186:189], v[18:21]
	v_mfma_f32_16x16x32_bf16 v[6:9], v[154:157], v[210:213], v[6:9]
	v_mfma_f32_16x16x32_bf16 v[2:5], v[162:165], v[210:213], v[2:5]
	s_setprio 0
	s_barrier
	s_add_u32 vcc_lo, vcc_lo, 0x100
	s_addc_u32 vcc_hi, vcc_hi, 0
	s_add_u32 s2, s2, 0x100
	s_addc_u32 s72, s72, 0
	s_cmp_ge_i32 s24, s68
	s_mov_b32 s8, s24
	s_cbranch_scc0 .LBB0_263
	s_mov_b32 s92, s3
	s_movk_i32 s93, 0x3fff
	s_movk_i32 s3, 0x2000
	s_and_b64 vcc, exec, s[44:45]
	s_cbranch_vccz .LBB0_266
